# attention: output-gate cache lines touched during the last key-tile iteration so the epilogue's gate loads hit cache
# speedup vs baseline: 1.0148x; 1.0022x over previous
; __device__ __forceinline__ void item_attn(const Params& p, int l, int aidx) {
;     ...
;     uint2 gz[2][4];
; #pragma unroll
;     for (int n = 0; n < 2; ++n) {
;       int row = 32 * wid + 16 * n + fr; if (row >= nq) row = nq - 1;
; #pragma unroll
;       for (int md = 0; md < 4; ++md) gz[n][md] = *reinterpret_cast<const uint2*>(p.gzc + (tokq0 + row) * 512 + hd * 64 + md * 16 + fq * 4);
;     }
.Lattn_touch:
	v_readlane_b32 s100, v247, 13
	v_readlane_b32 s101, v247, 14
	s_add_i32 s99, s47, -1
	s_add_u32 s100, s100, s44
	s_addc_u32 s101, s101, s45
	v_min_i32_e32 v236, s99, v84
	v_min_i32_e32 v238, s99, v86
	v_ashrrev_i32_e32 v237, 31, v236
	v_ashrrev_i32_e32 v239, 31, v238
	v_lshl_add_u64 v[236:237], s[34:35], 0, v[236:237]
	v_lshl_add_u64 v[238:239], s[34:35], 0, v[238:239]
	v_lshlrev_b64 v[236:237], 10, v[236:237]
	v_lshlrev_b64 v[238:239], 10, v[238:239]
	v_lshl_add_u64 v[236:237], s[100:101], 0, v[236:237]
	v_lshl_add_u64 v[238:239], s[100:101], 0, v[238:239]
	global_load_dword v234, v[236:237], off
	global_load_dword v235, v[238:239], off
	s_branch .LBB0_760

; __global__ void __launch_bounds__(NTHR) fwd_mega(Params p, int ph_lo, int ph_hi) {
	.amdhsa_kernel _Z8fwd_mega6Paramsii
		.amdhsa_group_segment_fixed_size 256
		.amdhsa_private_segment_fixed_size 0
		.amdhsa_kernarg_size 536
		.amdhsa_user_sgpr_count 2
		.amdhsa_user_sgpr_dispatch_ptr 0
		.amdhsa_user_sgpr_queue_ptr 0
		.amdhsa_user_sgpr_kernarg_segment_ptr 1
		.amdhsa_user_sgpr_dispatch_id 0
		.amdhsa_user_sgpr_kernarg_preload_length 0
		.amdhsa_user_sgpr_kernarg_preload_offset 0
		.amdhsa_user_sgpr_private_segment_size 0
		.amdhsa_uses_dynamic_stack 0
		.amdhsa_enable_private_segment 0
		.amdhsa_system_sgpr_workgroup_id_x 1
		.amdhsa_system_sgpr_workgroup_id_y 0
		.amdhsa_system_sgpr_workgroup_id_z 0
		.amdhsa_system_sgpr_workgroup_info 0
		.amdhsa_system_vgpr_workitem_id 2
		.amdhsa_next_free_vgpr 252
		.amdhsa_next_free_sgpr 102
		.amdhsa_accum_offset 252
		.amdhsa_reserve_vcc 1
		.amdhsa_float_round_mode_32 0
		.amdhsa_float_round_mode_16_64 0
		.amdhsa_float_denorm_mode_32 3
		.amdhsa_float_denorm_mode_16_64 3
		.amdhsa_dx10_clamp 1
		.amdhsa_ieee_mode 1
		.amdhsa_fp16_overflow 0
		.amdhsa_tg_split 0
		.amdhsa_exception_fp_ieee_invalid_op 0
		.amdhsa_exception_fp_denorm_src 0
		.amdhsa_exception_fp_ieee_div_zero 0
		.amdhsa_exception_fp_ieee_overflow 0
		.amdhsa_exception_fp_ieee_underflow 0
		.amdhsa_exception_fp_ieee_inexact 0
		.amdhsa_exception_int_div_zero 0
	.end_amdhsa_kernel

; __global__ void __launch_bounds__(NTHR) fwd_mega(Params p, int ph_lo, int ph_hi) {
amdhsa.kernels:
  - .agpr_count:     0
    .args:
      - .offset:         0
        .size:           272
        .value_kind:     by_value
      - .offset:         272
        .size:           4
        .value_kind:     by_value
      - .offset:         276
        .size:           4
        .value_kind:     by_value
      - .offset:         280
        .size:           4
        .value_kind:     hidden_block_count_x
      - .offset:         284
        .size:           4
        .value_kind:     hidden_block_count_y
      - .offset:         288
        .size:           4
        .value_kind:     hidden_block_count_z
      - .offset:         292
        .size:           2
        .value_kind:     hidden_group_size_x
      - .offset:         294
        .size:           2
        .value_kind:     hidden_group_size_y
      - .offset:         296
        .size:           2
        .value_kind:     hidden_group_size_z
      - .offset:         298
        .size:           2
        .value_kind:     hidden_remainder_x
      - .offset:         300
        .size:           2
        .value_kind:     hidden_remainder_y
      - .offset:         302
        .size:           2
        .value_kind:     hidden_remainder_z
      - .offset:         320
        .size:           8
        .value_kind:     hidden_global_offset_x
      - .offset:         328
        .size:           8
        .value_kind:     hidden_global_offset_y
      - .offset:         336
        .size:           8
        .value_kind:     hidden_global_offset_z
      - .offset:         344
        .size:           2
        .value_kind:     hidden_grid_dims
      - .offset:         368
        .size:           8
        .value_kind:     hidden_multigrid_sync_arg
      - .offset:         400
        .size:           4
        .value_kind:     hidden_dynamic_lds_size
    .group_segment_fixed_size: 256
    .kernarg_segment_align: 8
    .kernarg_segment_size: 536
    .language:       OpenCL C
    .language_version:
      - 2
      - 0
    .max_flat_workgroup_size: 512
    .name:           _Z8fwd_mega6Paramsii
    .private_segment_fixed_size: 0
    .sgpr_count:     108
    .sgpr_spill_count: 181
    .symbol:         _Z8fwd_mega6Paramsii.kd
    .uniform_work_group_size: 1
    .uses_dynamic_stack: false
    .vgpr_count:     252
    .vgpr_spill_count: 0
    .wavefront_size: 64
